# UPCONV K-loop: LDS fragment read addresses precomputed per tile (4 VALU adds out of every iteration)
# baseline (speedup 1.0000x reference)
; #define PG8_STAGE(bufoff, gbase, voff) do { _Pragma("unroll") for (int _i = 0; _i < 2; ++_i) \
;         __builtin_amdgcn_global_load_lds((const unsigned*)((const char*)(gbase) + (voff)[_i]), (PG8_LAS unsigned*)(lds + (bufoff) + ldsw + _i * 8192), 16, 0, 0); } while (0)
; #define PG8_LDA(dst, b, h) do { _Pragma("unroll") for (int m = 0; m < 4; ++m) _Pragma("unroll") for (int k = 0; k < 2; ++k) dst[m][k] = *(const PG8_LAS bf16x8*)(lds + PG8_SA(b, h) + aoff + m * 2048 + k * 1024); } while (0)
; #define PG8_LDB(dst, b, h) do { _Pragma("unroll") for (int n = 0; n < 2; ++n) _Pragma("unroll") for (int k = 0; k < 2; ++k) dst[n][k] = *(const PG8_LAS bf16x8*)(lds + PG8_SB(b, h) + boff + n * 2048 + k * 1024); } while (0)
; #define PG8_WAIT_V(n) asm volatile("s_waitcnt vmcnt(" #n ")" ::: "memory")
; #define PG8_WAIT_L(n) asm volatile("s_waitcnt lgkmcnt(" #n ")" ::: "memory")
; #define PG8_BAR __builtin_amdgcn_s_barrier()
; #define PG8_SCHED __builtin_amdgcn_sched_barrier(0)
; template <class Epi, class Sched, bool ALIGN_EPI = false, bool SP2 = false>
; __device__ __forceinline__ void gemm_phase(PG8_LAS unsigned char* lds, const Gemm g, const Sched& S, const Epi& E, int wave_in) {
;     ...
;         const char* nA = has_next ? (const char*)g.A + (size_t)nxt.pm * tstepA : cA; const char* nB = has_next ? (const char*)g.Bt + (size_t)nxt.pn * tstep : cB;
;         for (int t = 0; t < nt; t += 2) {
;             const bool last = (t == nt - 2);
;             const char* a1 = cA + (size_t)(t + 1) * kstep;
;             const char* a2 = last ? nA : cA + (size_t)(t + 2) * kstep; const char* b2 = last ? nB : cB + (size_t)(t + 2) * kstep;
;             const char* a3 = a2 + kstep; const char* b3 = b2 + kstep;
;             if (last && has_next) S.a_ready(nxt);
;             if constexpr (SP2) {
;             PG8_LDB(B0, 0, 0); PG8_LDB(B1, 0, 1); PG8_SCHED; PG8_LDA(At, 0, 0); PG8_STAGE(PG8_SA(1, 1), a1 + hstepA, voffA);
;             PG8_WAIT_V(8); PG8_WAIT_L(0); PG8_BAR; PG8_MMA(0, 0, At, B0); PG8_MMA(0, 1, At, B1); PG8_BAR; PG8_SCHED;
;     ...
; #pragma unroll
;         for (int a = 0; a < 2; ++a)
; #pragma unroll
;             for (int b = 0; b < 2; ++b)
; #pragma unroll
;                 for (int m = 0; m < 4; ++m)
; #pragma unroll
;                     for (int n = 0; n < 2; ++n) acc[a][b][m][n] = (f32x4){0.f, 0.f, 0.f, 0.f};
;         cur = nxt; cA = nA; cB = nB; ++ui;
.LBB0_42:
	s_ashr_i32 s43, s42, 31
	s_lshl_b64 s[44:45], s[42:43], 20
	v_readlane_b32 s46, v253, 60
	v_readlane_b32 s47, v253, 61
	s_add_u32 s44, s46, s44
	s_addc_u32 s45, s47, s45
	s_and_b64 s[46:47], s[8:9], exec
	s_cselect_b32 s43, s45, s49
	s_cselect_b32 s67, s44, s48
	s_ashr_i32 s41, s40, 31
	s_lshl_b64 s[46:47], s[40:41], 20
	s_add_u32 s46, s54, s46
	s_addc_u32 s47, s55, s47
	s_and_b64 s[52:53], s[8:9], exec
	s_cselect_b32 s41, s47, s51
	s_cselect_b32 s68, s46, s50
	s_add_u32 s48, s48, 0x80080
	s_addc_u32 s49, s49, 0
	s_add_u32 s69, s50, 0x100
	v_mov_b32_e32 v2, 0
	s_addc_u32 s70, s51, 0
	s_mov_b32 s71, -2
	v_mov_b32_e32 v3, v2
	v_mov_b32_e32 v4, v2
	v_mov_b32_e32 v5, v2
	v_mov_b32_e32 v66, v2
	v_mov_b32_e32 v67, v2
	v_mov_b32_e32 v68, v2
	v_mov_b32_e32 v69, v2
	v_mov_b32_e32 v10, v2
	v_mov_b32_e32 v11, v2
	v_mov_b32_e32 v12, v2
	v_mov_b32_e32 v13, v2
	v_mov_b32_e32 v74, v2
	v_mov_b32_e32 v75, v2
	v_mov_b32_e32 v76, v2
	v_mov_b32_e32 v77, v2
	v_mov_b32_e32 v18, v2
	v_mov_b32_e32 v19, v2
	s_waitcnt vmcnt(0)
	v_mov_b32_e32 v20, v2
	v_mov_b32_e32 v21, v2
	v_mov_b32_e32 v82, v2
	v_mov_b32_e32 v83, v2
	v_mov_b32_e32 v84, v2
	v_mov_b32_e32 v85, v2
	v_mov_b32_e32 v26, v2
	v_mov_b32_e32 v27, v2
	v_mov_b32_e32 v28, v2
	v_mov_b32_e32 v29, v2
	v_mov_b32_e32 v90, v2
	v_mov_b32_e32 v91, v2
	v_mov_b32_e32 v92, v2
	v_mov_b32_e32 v93, v2
	v_mov_b32_e32 v6, v2
	v_mov_b32_e32 v7, v2
	v_mov_b32_e32 v8, v2
	v_mov_b32_e32 v9, v2
	v_mov_b32_e32 v70, v2
	v_mov_b32_e32 v71, v2
	v_mov_b32_e32 v72, v2
	v_mov_b32_e32 v73, v2
	v_mov_b32_e32 v14, v2
	v_mov_b32_e32 v15, v2
	v_mov_b32_e32 v16, v2
	v_mov_b32_e32 v17, v2
	v_mov_b32_e32 v78, v2
	v_mov_b32_e32 v79, v2
	v_mov_b32_e32 v80, v2
	v_mov_b32_e32 v81, v2
	v_mov_b32_e32 v22, v2
	v_mov_b32_e32 v23, v2
	v_mov_b32_e32 v24, v2
	v_mov_b32_e32 v25, v2
	v_mov_b32_e32 v86, v2
	v_mov_b32_e32 v87, v2
	v_mov_b32_e32 v88, v2
	v_mov_b32_e32 v89, v2
	v_mov_b32_e32 v30, v2
	v_mov_b32_e32 v31, v2
	v_mov_b32_e32 v32, v2
	v_mov_b32_e32 v33, v2
	v_mov_b32_e32 v94, v2
	v_mov_b32_e32 v95, v2
	v_mov_b32_e32 v96, v2
	v_mov_b32_e32 v97, v2
	v_mov_b32_e32 v34, v2
	v_mov_b32_e32 v35, v2
	v_mov_b32_e32 v36, v2
	v_mov_b32_e32 v37, v2
	v_mov_b32_e32 v98, v2
	v_mov_b32_e32 v99, v2
	v_mov_b32_e32 v100, v2
	v_mov_b32_e32 v101, v2
	v_mov_b32_e32 v42, v2
	v_mov_b32_e32 v43, v2
	v_mov_b32_e32 v44, v2
	v_mov_b32_e32 v45, v2
	v_mov_b32_e32 v138, v2
	v_mov_b32_e32 v139, v2
	v_mov_b32_e32 v140, v2
	v_mov_b32_e32 v141, v2
	v_mov_b32_e32 v50, v2
	v_mov_b32_e32 v51, v2
	v_mov_b32_e32 v52, v2
	v_mov_b32_e32 v53, v2
	v_mov_b32_e32 v146, v2
	v_mov_b32_e32 v147, v2
	v_mov_b32_e32 v148, v2
	v_mov_b32_e32 v149, v2
	v_mov_b32_e32 v58, v2
	v_mov_b32_e32 v59, v2
	v_mov_b32_e32 v60, v2
	v_mov_b32_e32 v61, v2
	v_mov_b32_e32 v134, v2
	v_mov_b32_e32 v135, v2
	v_mov_b32_e32 v136, v2
	v_mov_b32_e32 v137, v2
	v_mov_b32_e32 v38, v2
	v_mov_b32_e32 v39, v2
	v_mov_b32_e32 v40, v2
	v_mov_b32_e32 v41, v2
	v_mov_b32_e32 v102, v2
	v_mov_b32_e32 v103, v2
	v_mov_b32_e32 v104, v2
	v_mov_b32_e32 v105, v2
	v_mov_b32_e32 v46, v2
	v_mov_b32_e32 v47, v2
	v_mov_b32_e32 v48, v2
	v_mov_b32_e32 v49, v2
	v_mov_b32_e32 v142, v2
	v_mov_b32_e32 v143, v2
	v_mov_b32_e32 v144, v2
	v_mov_b32_e32 v145, v2
	v_mov_b32_e32 v54, v2
	v_mov_b32_e32 v55, v2
	v_mov_b32_e32 v56, v2
	v_mov_b32_e32 v57, v2
	v_mov_b32_e32 v150, v2
	v_mov_b32_e32 v151, v2
	v_mov_b32_e32 v152, v2
	v_mov_b32_e32 v153, v2
	v_mov_b32_e32 v62, v2
	v_mov_b32_e32 v63, v2
	v_mov_b32_e32 v64, v2
	v_mov_b32_e32 v65, v2
	v_mov_b32_e32 v154, v2
	v_mov_b32_e32 v155, v2
	v_mov_b32_e32 v156, v2
	v_mov_b32_e32 v157, v2
	v_add_u32_e32 v238, 0x10000, v214
	v_add_u32_e32 v239, 0x14000, v214
	v_add_u32_e32 v240, 0x18000, v214
	v_add_u32_e32 v241, 0x1c000, v214
	s_nop 0
	s_nop 0
.LBB0_43:
	s_add_u32 s50, s48, 0xfff80080
	s_addc_u32 s51, s49, -1
	s_add_i32 s72, 0, 0x10000
	s_cmp_eq_u32 s71, 28
	s_cselect_b32 s53, s43, s51
	s_cselect_b32 s52, s67, s50
	s_cselect_b32 s51, s41, s70
	s_cselect_b32 s50, s68, s69
	s_add_i32 s74, 0, 0x14000
	ds_read_b128 v[106:109], v238
	ds_read_b128 v[110:113], v238 offset:1024
	ds_read_b128 v[114:117], v238 offset:2048
	ds_read_b128 v[118:121], v238 offset:3072
	ds_read_b128 v[122:125], v239
	ds_read_b128 v[126:129], v239 offset:1024
	ds_read_b128 v[130:133], v239 offset:2048
	ds_read_b128 v[178:181], v239 offset:3072
	s_add_i32 m0, s58, 0xc000
	ds_read_b128 v[182:185], v217
	ds_read_b128 v[186:189], v217 offset:1024
	ds_read_b128 v[190:193], v217 offset:2048
	ds_read_b128 v[218:221], v217 offset:3072
	ds_read_b128 v[222:225], v217 offset:4096
	ds_read_b128 v[226:229], v217 offset:5120
	ds_read_b128 v[230:233], v217 offset:6144
	ds_read_b128 v[234:237], v217 offset:7168
	global_load_lds_dwordx4 v174, s[48:49]
	s_add_i32 m0, s58, 0xe000
	s_nop 0
	global_load_lds_dwordx4 v176, s[48:49]
	s_waitcnt vmcnt(8)
	s_waitcnt lgkmcnt(0)
	s_barrier
; #define PG8_STAGE(bufoff, gbase, voff) do { _Pragma("unroll") for (int _i = 0; _i < 2; ++_i) \
;         __builtin_amdgcn_global_load_lds((const unsigned*)((const char*)(gbase) + (voff)[_i]), (PG8_LAS unsigned*)(lds + (bufoff) + ldsw + _i * 8192), 16, 0, 0); } while (0)
; #define PG8_LDA(dst, b, h) do { _Pragma("unroll") for (int m = 0; m < 4; ++m) _Pragma("unroll") for (int k = 0; k < 2; ++k) dst[m][k] = *(const PG8_LAS bf16x8*)(lds + PG8_SA(b, h) + aoff + m * 2048 + k * 1024); } while (0)
; #define PG8_MMA(ai, bj, At, Bt) do { __builtin_amdgcn_s_setprio(1); _Pragma("unroll") for (int m = 0; m < 4; ++m) _Pragma("unroll") for (int n = 0; n < 2; ++n) _Pragma("unroll") for (int k = 0; k < 2; ++k) \
;         acc[ai][bj][m][n] = __builtin_amdgcn_mfma_f32_16x16x32_bf16(Bt[n][k], At[m][k], acc[ai][bj][m][n], 0, 0, 0); __builtin_amdgcn_s_setprio(0); } while (0)
; #define PG8_WAIT_V(n) asm volatile("s_waitcnt vmcnt(" #n ")" ::: "memory")
; #define PG8_WAIT_L(n) asm volatile("s_waitcnt lgkmcnt(" #n ")" ::: "memory")
; #define PG8_BAR __builtin_amdgcn_s_barrier()
; #define PG8_SCHED __builtin_amdgcn_sched_barrier(0)
; template <class Epi, class Sched, bool ALIGN_EPI = false, bool SP2 = false>
; __device__ __forceinline__ void gemm_phase(PG8_LAS unsigned char* lds, const Gemm g, const Sched& S, const Epi& E, int wave_in) {
;     ...
;             PG8_WAIT_V(8); PG8_WAIT_L(0); PG8_BAR; PG8_MMA(0, 0, At, B0); PG8_MMA(0, 1, At, B1); PG8_BAR; PG8_SCHED;
;             PG8_LDA(At, 0, 1); PG8_STAGE(PG8_SB(0, 0), b2, voffB); PG8_STAGE(PG8_SB(0, 1), b2 + hstep, voffB); PG8_STAGE(PG8_SA(0, 0), a2, voffA);
;             PG8_WAIT_V(8); PG8_WAIT_L(0); PG8_BAR; PG8_MMA(1, 0, At, B0); PG8_MMA(1, 1, At, B1); PG8_BAR; PG8_SCHED;
	s_waitcnt lgkmcnt(0)
	v_mfma_f32_16x16x32_bf16 v[154:157], v[106:109], v[182:185], v[154:157]
	v_mfma_f32_16x16x32_bf16 v[62:65], v[114:117], v[182:185], v[62:65]
	v_mfma_f32_16x16x32_bf16 v[150:153], v[106:109], v[190:193], v[150:153]
	v_mfma_f32_16x16x32_bf16 v[54:57], v[114:117], v[190:193], v[54:57]
	v_mfma_f32_16x16x32_bf16 v[142:145], v[106:109], v[222:225], v[142:145]
	v_mfma_f32_16x16x32_bf16 v[46:49], v[114:117], v[222:225], v[46:49]
	v_mfma_f32_16x16x32_bf16 v[102:105], v[106:109], v[230:233], v[102:105]
	v_mfma_f32_16x16x32_bf16 v[38:41], v[114:117], v[230:233], v[38:41]
	v_mfma_f32_16x16x32_bf16 v[154:157], v[110:113], v[186:189], v[154:157]
	v_mfma_f32_16x16x32_bf16 v[62:65], v[118:121], v[186:189], v[62:65]
	v_mfma_f32_16x16x32_bf16 v[150:153], v[110:113], v[218:221], v[150:153]
	v_mfma_f32_16x16x32_bf16 v[54:57], v[118:121], v[218:221], v[54:57]
	v_mfma_f32_16x16x32_bf16 v[142:145], v[110:113], v[226:229], v[142:145]
	v_mfma_f32_16x16x32_bf16 v[46:49], v[118:121], v[226:229], v[46:49]
	v_mfma_f32_16x16x32_bf16 v[102:105], v[110:113], v[234:237], v[102:105]
	v_mfma_f32_16x16x32_bf16 v[38:41], v[118:121], v[234:237], v[38:41]
	v_mfma_f32_16x16x32_bf16 v[134:137], v[122:125], v[182:185], v[134:137]
	v_mfma_f32_16x16x32_bf16 v[58:61], v[130:133], v[182:185], v[58:61]
	v_mfma_f32_16x16x32_bf16 v[146:149], v[122:125], v[190:193], v[146:149]
	v_mfma_f32_16x16x32_bf16 v[50:53], v[130:133], v[190:193], v[50:53]
	v_mfma_f32_16x16x32_bf16 v[138:141], v[122:125], v[222:225], v[138:141]
	v_mfma_f32_16x16x32_bf16 v[42:45], v[130:133], v[222:225], v[42:45]
	v_mfma_f32_16x16x32_bf16 v[98:101], v[122:125], v[230:233], v[98:101]
	v_mfma_f32_16x16x32_bf16 v[34:37], v[130:133], v[230:233], v[34:37]
	v_mfma_f32_16x16x32_bf16 v[134:137], v[126:129], v[186:189], v[134:137]
	v_mfma_f32_16x16x32_bf16 v[58:61], v[178:181], v[186:189], v[58:61]
	v_mfma_f32_16x16x32_bf16 v[146:149], v[126:129], v[218:221], v[146:149]
	v_mfma_f32_16x16x32_bf16 v[50:53], v[178:181], v[218:221], v[50:53]
	v_mfma_f32_16x16x32_bf16 v[138:141], v[126:129], v[226:229], v[138:141]
	v_mfma_f32_16x16x32_bf16 v[42:45], v[178:181], v[226:229], v[42:45]
	v_mfma_f32_16x16x32_bf16 v[98:101], v[126:129], v[234:237], v[98:101]
	v_mfma_f32_16x16x32_bf16 v[34:37], v[178:181], v[234:237], v[34:37]
	s_barrier
	s_add_i32 s72, s72, s57
	s_add_u32 vcc_lo, s50, s84
	s_addc_u32 vcc_hi, s51, s85
	s_mov_b32 m0, s72
	ds_read_b128 v[182:185], v217 offset:16384
	ds_read_b128 v[186:189], v217 offset:17408
	ds_read_b128 v[190:193], v217 offset:18432
	ds_read_b128 v[218:221], v217 offset:19456
	ds_read_b128 v[222:225], v217 offset:20480
	ds_read_b128 v[226:229], v217 offset:21504
	ds_read_b128 v[230:233], v217 offset:22528
	ds_read_b128 v[234:237], v217 offset:23552
	global_load_lds_dwordx4 v0, s[50:51]
	s_add_i32 m0, s72, 0x2000
	s_add_u32 s72, s50, 0x80000
	s_addc_u32 s73, s51, 0
	s_add_i32 s74, s74, s57
	global_load_lds_dwordx4 v168, s[50:51]
	s_mov_b32 m0, s74
	s_add_u32 s98, s52, s84
	s_addc_u32 s99, s53, s85
	global_load_lds_dwordx4 v0, s[72:73]
	s_add_i32 m0, s74, 0x2000
	s_nop 0
	global_load_lds_dwordx4 v168, s[72:73]
	s_mov_b32 m0, s58
	s_nop 0
	global_load_lds_dwordx4 v172, s[52:53]
	s_mov_b32 m0, s59
	s_nop 0
	global_load_lds_dwordx4 v170, s[52:53]
	s_waitcnt vmcnt(8)
	s_waitcnt lgkmcnt(0)
	s_barrier
	s_waitcnt lgkmcnt(0)
	v_mfma_f32_16x16x32_bf16 v[94:97], v[106:109], v[182:185], v[94:97]
	v_mfma_f32_16x16x32_bf16 v[30:33], v[114:117], v[182:185], v[30:33]
	v_mfma_f32_16x16x32_bf16 v[86:89], v[106:109], v[190:193], v[86:89]
	v_mfma_f32_16x16x32_bf16 v[22:25], v[114:117], v[190:193], v[22:25]
	v_mfma_f32_16x16x32_bf16 v[78:81], v[106:109], v[222:225], v[78:81]
	v_mfma_f32_16x16x32_bf16 v[14:17], v[114:117], v[222:225], v[14:17]
	v_mfma_f32_16x16x32_bf16 v[70:73], v[106:109], v[230:233], v[70:73]
	v_mfma_f32_16x16x32_bf16 v[6:9], v[114:117], v[230:233], v[6:9]
	v_mfma_f32_16x16x32_bf16 v[94:97], v[110:113], v[186:189], v[94:97]
	v_mfma_f32_16x16x32_bf16 v[30:33], v[118:121], v[186:189], v[30:33]
	v_mfma_f32_16x16x32_bf16 v[86:89], v[110:113], v[218:221], v[86:89]
	v_mfma_f32_16x16x32_bf16 v[22:25], v[118:121], v[218:221], v[22:25]
	v_mfma_f32_16x16x32_bf16 v[78:81], v[110:113], v[226:229], v[78:81]
	v_mfma_f32_16x16x32_bf16 v[14:17], v[118:121], v[226:229], v[14:17]
	v_mfma_f32_16x16x32_bf16 v[70:73], v[110:113], v[234:237], v[70:73]
	v_mfma_f32_16x16x32_bf16 v[6:9], v[118:121], v[234:237], v[6:9]
	v_mfma_f32_16x16x32_bf16 v[90:93], v[122:125], v[182:185], v[90:93]
	v_mfma_f32_16x16x32_bf16 v[26:29], v[130:133], v[182:185], v[26:29]
	v_mfma_f32_16x16x32_bf16 v[82:85], v[122:125], v[190:193], v[82:85]
	v_mfma_f32_16x16x32_bf16 v[18:21], v[130:133], v[190:193], v[18:21]
	v_mfma_f32_16x16x32_bf16 v[74:77], v[122:125], v[222:225], v[74:77]
	v_mfma_f32_16x16x32_bf16 v[10:13], v[130:133], v[222:225], v[10:13]
	v_mfma_f32_16x16x32_bf16 v[66:69], v[122:125], v[230:233], v[66:69]
	v_mfma_f32_16x16x32_bf16 v[2:5], v[130:133], v[230:233], v[2:5]
	v_mfma_f32_16x16x32_bf16 v[90:93], v[126:129], v[186:189], v[90:93]
	v_mfma_f32_16x16x32_bf16 v[26:29], v[178:181], v[186:189], v[26:29]
	v_mfma_f32_16x16x32_bf16 v[82:85], v[126:129], v[218:221], v[82:85]
	v_mfma_f32_16x16x32_bf16 v[18:21], v[178:181], v[218:221], v[18:21]
	v_mfma_f32_16x16x32_bf16 v[74:77], v[126:129], v[226:229], v[74:77]
	v_mfma_f32_16x16x32_bf16 v[10:13], v[178:181], v[226:229], v[10:13]
	v_mfma_f32_16x16x32_bf16 v[66:69], v[126:129], v[234:237], v[66:69]
	v_mfma_f32_16x16x32_bf16 v[2:5], v[178:181], v[234:237], v[2:5]
	s_barrier
; #define PG8_STAGE(bufoff, gbase, voff) do { _Pragma("unroll") for (int _i = 0; _i < 2; ++_i) \
;         __builtin_amdgcn_global_load_lds((const unsigned*)((const char*)(gbase) + (voff)[_i]), (PG8_LAS unsigned*)(lds + (bufoff) + ldsw + _i * 8192), 16, 0, 0); } while (0)
; #define PG8_LDA(dst, b, h) do { _Pragma("unroll") for (int m = 0; m < 4; ++m) _Pragma("unroll") for (int k = 0; k < 2; ++k) dst[m][k] = *(const PG8_LAS bf16x8*)(lds + PG8_SA(b, h) + aoff + m * 2048 + k * 1024); } while (0)
; #define PG8_LDB(dst, b, h) do { _Pragma("unroll") for (int n = 0; n < 2; ++n) _Pragma("unroll") for (int k = 0; k < 2; ++k) dst[n][k] = *(const PG8_LAS bf16x8*)(lds + PG8_SB(b, h) + boff + n * 2048 + k * 1024); } while (0)
; #define PG8_MMA(ai, bj, At, Bt) do { __builtin_amdgcn_s_setprio(1); _Pragma("unroll") for (int m = 0; m < 4; ++m) _Pragma("unroll") for (int n = 0; n < 2; ++n) _Pragma("unroll") for (int k = 0; k < 2; ++k) \
;         acc[ai][bj][m][n] = __builtin_amdgcn_mfma_f32_16x16x32_bf16(Bt[n][k], At[m][k], acc[ai][bj][m][n], 0, 0, 0); __builtin_amdgcn_s_setprio(0); } while (0)
; #define PG8_WAIT_V(n) asm volatile("s_waitcnt vmcnt(" #n ")" ::: "memory")
; #define PG8_WAIT_L(n) asm volatile("s_waitcnt lgkmcnt(" #n ")" ::: "memory")
; #define PG8_BAR __builtin_amdgcn_s_barrier()
; template <class Epi, class Sched, bool ALIGN_EPI = false, bool SP2 = false>
; __device__ __forceinline__ void gemm_phase(PG8_LAS unsigned char* lds, const Gemm g, const Sched& S, const Epi& E, int wave_in) {
;     ...
;         for (int t = 0; t < nt; t += 2) {
;             const bool last = (t == nt - 2);
;             const char* a1 = cA + (size_t)(t + 1) * kstep;
;             const char* a2 = last ? nA : cA + (size_t)(t + 2) * kstep; const char* b2 = last ? nB : cB + (size_t)(t + 2) * kstep;
;             const char* a3 = a2 + kstep; const char* b3 = b2 + kstep;
;     ...
;             PG8_LDB(B0, 1, 0); PG8_LDB(B1, 1, 1); PG8_SCHED; PG8_LDA(At, 1, 0); PG8_STAGE(PG8_SA(0, 1), a2 + hstepA, voffA);
;             PG8_WAIT_V(8); PG8_WAIT_L(0); PG8_BAR; PG8_MMA(0, 0, At, B0); PG8_MMA(0, 1, At, B1); PG8_BAR; PG8_SCHED;
;             PG8_LDA(At, 1, 1); PG8_STAGE(PG8_SB(1, 0), b3, voffB); PG8_STAGE(PG8_SB(1, 1), b3 + hstep, voffB); PG8_STAGE(PG8_SA(1, 0), a3, voffA);
;             PG8_WAIT_V(8); PG8_WAIT_L(0); PG8_BAR; PG8_MMA(1, 0, At, B0); PG8_MMA(1, 1, At, B1); PG8_BAR; PG8_SCHED;
	s_add_i32 s72, 0, 0x18000
	s_add_i32 s73, 0, 0x1c000
	ds_read_b128 v[106:109], v240
	ds_read_b128 v[110:113], v240 offset:1024
	ds_read_b128 v[114:117], v240 offset:2048
	ds_read_b128 v[118:121], v240 offset:3072
	ds_read_b128 v[122:125], v241
	ds_read_b128 v[126:129], v241 offset:1024
	ds_read_b128 v[130:133], v241 offset:2048
	ds_read_b128 v[178:181], v241 offset:3072
	s_add_u32 s52, s52, 0x80000
	s_addc_u32 s53, s53, 0
	s_mov_b32 m0, s60
	ds_read_b128 v[182:185], v217 offset:32768
	ds_read_b128 v[186:189], v217 offset:33792
	ds_read_b128 v[190:193], v217 offset:34816
	ds_read_b128 v[218:221], v217 offset:35840
	ds_read_b128 v[222:225], v217 offset:36864
	ds_read_b128 v[226:229], v217 offset:37888
	ds_read_b128 v[230:233], v217 offset:38912
	ds_read_b128 v[234:237], v217 offset:39936
	global_load_lds_dwordx4 v172, s[52:53]
	s_mov_b32 m0, s61
	s_nop 0
	global_load_lds_dwordx4 v170, s[52:53]
	s_waitcnt vmcnt(8)
	s_waitcnt lgkmcnt(0)
	s_barrier
	s_waitcnt lgkmcnt(0)
	v_mfma_f32_16x16x32_bf16 v[154:157], v[106:109], v[182:185], v[154:157]
	v_mfma_f32_16x16x32_bf16 v[62:65], v[114:117], v[182:185], v[62:65]
	v_mfma_f32_16x16x32_bf16 v[150:153], v[106:109], v[190:193], v[150:153]
	v_mfma_f32_16x16x32_bf16 v[54:57], v[114:117], v[190:193], v[54:57]
	v_mfma_f32_16x16x32_bf16 v[142:145], v[106:109], v[222:225], v[142:145]
	v_mfma_f32_16x16x32_bf16 v[46:49], v[114:117], v[222:225], v[46:49]
	v_mfma_f32_16x16x32_bf16 v[102:105], v[106:109], v[230:233], v[102:105]
	v_mfma_f32_16x16x32_bf16 v[38:41], v[114:117], v[230:233], v[38:41]
	v_mfma_f32_16x16x32_bf16 v[154:157], v[110:113], v[186:189], v[154:157]
	v_mfma_f32_16x16x32_bf16 v[62:65], v[118:121], v[186:189], v[62:65]
	v_mfma_f32_16x16x32_bf16 v[150:153], v[110:113], v[218:221], v[150:153]
	v_mfma_f32_16x16x32_bf16 v[54:57], v[118:121], v[218:221], v[54:57]
	v_mfma_f32_16x16x32_bf16 v[142:145], v[110:113], v[226:229], v[142:145]
	v_mfma_f32_16x16x32_bf16 v[46:49], v[118:121], v[226:229], v[46:49]
	v_mfma_f32_16x16x32_bf16 v[102:105], v[110:113], v[234:237], v[102:105]
	v_mfma_f32_16x16x32_bf16 v[38:41], v[118:121], v[234:237], v[38:41]
	v_mfma_f32_16x16x32_bf16 v[134:137], v[122:125], v[182:185], v[134:137]
	v_mfma_f32_16x16x32_bf16 v[58:61], v[130:133], v[182:185], v[58:61]
	v_mfma_f32_16x16x32_bf16 v[146:149], v[122:125], v[190:193], v[146:149]
	v_mfma_f32_16x16x32_bf16 v[50:53], v[130:133], v[190:193], v[50:53]
	v_mfma_f32_16x16x32_bf16 v[138:141], v[122:125], v[222:225], v[138:141]
	v_mfma_f32_16x16x32_bf16 v[42:45], v[130:133], v[222:225], v[42:45]
	v_mfma_f32_16x16x32_bf16 v[98:101], v[122:125], v[230:233], v[98:101]
	v_mfma_f32_16x16x32_bf16 v[34:37], v[130:133], v[230:233], v[34:37]
	v_mfma_f32_16x16x32_bf16 v[134:137], v[126:129], v[186:189], v[134:137]
	v_mfma_f32_16x16x32_bf16 v[58:61], v[178:181], v[186:189], v[58:61]
	v_mfma_f32_16x16x32_bf16 v[146:149], v[126:129], v[218:221], v[146:149]
	v_mfma_f32_16x16x32_bf16 v[50:53], v[178:181], v[218:221], v[50:53]
	v_mfma_f32_16x16x32_bf16 v[138:141], v[126:129], v[226:229], v[138:141]
	v_mfma_f32_16x16x32_bf16 v[42:45], v[178:181], v[226:229], v[42:45]
	v_mfma_f32_16x16x32_bf16 v[98:101], v[126:129], v[234:237], v[98:101]
	v_mfma_f32_16x16x32_bf16 v[34:37], v[178:181], v[234:237], v[34:37]
	s_barrier
	s_add_i32 s52, s72, s57
	s_mov_b32 m0, s52
	ds_read_b128 v[182:185], v217 offset:49152
	ds_read_b128 v[186:189], v217 offset:50176
	ds_read_b128 v[190:193], v217 offset:51200
	ds_read_b128 v[218:221], v217 offset:52224
	ds_read_b128 v[222:225], v217 offset:53248
	ds_read_b128 v[226:229], v217 offset:54272
	ds_read_b128 v[230:233], v217 offset:55296
	ds_read_b128 v[234:237], v217 offset:56320
	global_load_lds_dwordx4 v0, vcc
	s_add_i32 m0, s52, 0x2000
	s_add_u32 s50, s50, 0x80080
	s_addc_u32 s51, s51, 0
	s_add_i32 s52, s73, s57
	global_load_lds_dwordx4 v168, vcc
	s_mov_b32 m0, s52
	s_nop 0
	global_load_lds_dwordx4 v0, s[50:51]
	s_add_i32 m0, s52, 0x2000
	s_nop 0
	global_load_lds_dwordx4 v168, s[50:51]
	s_mov_b32 m0, s62
	s_nop 0
	global_load_lds_dwordx4 v172, s[98:99]
	s_mov_b32 m0, s63
	s_nop 0
	global_load_lds_dwordx4 v170, s[98:99]
	s_waitcnt vmcnt(8)
	s_waitcnt lgkmcnt(0)
	s_barrier
	s_waitcnt lgkmcnt(0)
	v_mfma_f32_16x16x32_bf16 v[94:97], v[106:109], v[182:185], v[94:97]
	v_mfma_f32_16x16x32_bf16 v[30:33], v[114:117], v[182:185], v[30:33]
	v_mfma_f32_16x16x32_bf16 v[86:89], v[106:109], v[190:193], v[86:89]
	v_mfma_f32_16x16x32_bf16 v[22:25], v[114:117], v[190:193], v[22:25]
	v_mfma_f32_16x16x32_bf16 v[78:81], v[106:109], v[222:225], v[78:81]
	v_mfma_f32_16x16x32_bf16 v[14:17], v[114:117], v[222:225], v[14:17]
	v_mfma_f32_16x16x32_bf16 v[70:73], v[106:109], v[230:233], v[70:73]
	v_mfma_f32_16x16x32_bf16 v[6:9], v[114:117], v[230:233], v[6:9]
	v_mfma_f32_16x16x32_bf16 v[94:97], v[110:113], v[186:189], v[94:97]
	v_mfma_f32_16x16x32_bf16 v[30:33], v[118:121], v[186:189], v[30:33]
	v_mfma_f32_16x16x32_bf16 v[86:89], v[110:113], v[218:221], v[86:89]
	v_mfma_f32_16x16x32_bf16 v[22:25], v[118:121], v[218:221], v[22:25]
	v_mfma_f32_16x16x32_bf16 v[78:81], v[110:113], v[226:229], v[78:81]
	v_mfma_f32_16x16x32_bf16 v[14:17], v[118:121], v[226:229], v[14:17]
	v_mfma_f32_16x16x32_bf16 v[70:73], v[110:113], v[234:237], v[70:73]
	v_mfma_f32_16x16x32_bf16 v[6:9], v[118:121], v[234:237], v[6:9]
	v_mfma_f32_16x16x32_bf16 v[90:93], v[122:125], v[182:185], v[90:93]
	v_mfma_f32_16x16x32_bf16 v[26:29], v[130:133], v[182:185], v[26:29]
	v_mfma_f32_16x16x32_bf16 v[82:85], v[122:125], v[190:193], v[82:85]
	v_mfma_f32_16x16x32_bf16 v[18:21], v[130:133], v[190:193], v[18:21]
	v_mfma_f32_16x16x32_bf16 v[74:77], v[122:125], v[222:225], v[74:77]
	v_mfma_f32_16x16x32_bf16 v[10:13], v[130:133], v[222:225], v[10:13]
	v_mfma_f32_16x16x32_bf16 v[66:69], v[122:125], v[230:233], v[66:69]
	v_mfma_f32_16x16x32_bf16 v[2:5], v[130:133], v[230:233], v[2:5]
	v_mfma_f32_16x16x32_bf16 v[90:93], v[126:129], v[186:189], v[90:93]
	v_mfma_f32_16x16x32_bf16 v[26:29], v[178:181], v[186:189], v[26:29]
	v_mfma_f32_16x16x32_bf16 v[82:85], v[126:129], v[218:221], v[82:85]
	v_mfma_f32_16x16x32_bf16 v[18:21], v[178:181], v[218:221], v[18:21]
	v_mfma_f32_16x16x32_bf16 v[74:77], v[126:129], v[226:229], v[74:77]
	v_mfma_f32_16x16x32_bf16 v[10:13], v[178:181], v[226:229], v[10:13]
	v_mfma_f32_16x16x32_bf16 v[66:69], v[126:129], v[234:237], v[66:69]
	v_mfma_f32_16x16x32_bf16 v[2:5], v[178:181], v[234:237], v[2:5]
	s_barrier
	s_add_i32 s71, s71, 2
	s_add_u32 s48, s48, 0x100
	s_addc_u32 s49, s49, 0
	s_add_u32 s69, s69, 0x100
	s_addc_u32 s70, s70, 0
	s_cmp_gt_u32 s71, 29
	s_cbranch_scc0 .LBB0_43
	s_and_b64 vcc, exec, s[24:25]
	s_cbranch_vccz .LBB0_46
	s_barrier
